# packed f32 adds of the block-mean accumulation inside the GEMM1 k-loop split into scalar v_add_f32 pairs (bit-identical)
# baseline (speedup 1.0000x reference)
; DI f32x16 mfma32(bf16x8 a, bf16x8 b, f32x16 c) { return __builtin_amdgcn_mfma_f32_32x32x16_bf16(a, b, c, 0, 0, 0); }
; DI void kmean_item(const float* __restrict__ base, const int* __restrict__ pt, int b, int n, float* __restrict__ outp, char* sm) {
;     ...
;         for (int rr = 0; rr < 32; ++rr) {
;             a0 += __builtin_nontemporal_load((const f32x4*)(rp + (size_t)rr * 4096));
;             a1 += __builtin_nontemporal_load((const f32x4*)(rp + (size_t)rr * 4096 + 256));
;         }
; template <class AL>
; DI void gemm_mainloop(f32x16 (&acc)[2][2], GemmRegs<AL>& G, bool pre, const AL& al, const u16* __restrict__ Bt, int ldb, int n0, int nk, char* sm,
;                       bool has_next, const AL& aln, int n0n) {
;     ...
;         auto rd = [&](int set, int ks) {
; #pragma unroll
;             for (int mi = 0; mi < 2; ++mi) { const int row = wm * 64 + mi * 32 + r; a[set][mi] = *(const bf16x8*)(cA + row * 128 + (((2 * ks + h) ^ ((row >> 1) & 7)) << 4)); }
; #pragma unroll
;             for (int ni = 0; ni < 2; ++ni) { const int row = wn * 64 + ni * 32 + r; b[set][ni] = *(const bf16x8*)(cB + row * 128 + (((2 * ks + h) ^ ((row >> 1) & 7)) << 4)); }
;         };
;         auto mm = [&](int set) {
; #pragma unroll
;             for (int mi = 0; mi < 2; ++mi)
; #pragma unroll
;                 for (int ni = 0; ni < 2; ++ni) acc[mi][ni] = mfma32(a[set][mi], b[set][ni], acc[mi][ni]);
;         };
;         rd(0, 0); rd(1, 1);
;         __builtin_amdgcn_sched_barrier(0);
;         mm(0); rd(0, 2);
;         __builtin_amdgcn_sched_barrier(0);
;         mm(1); rd(1, 3);
;         __builtin_amdgcn_sched_barrier(0);
;         mm(0); mm(1);
.Lg1_loop:
	s_setprio 1
	v_add_u32_e32 v174, v168, v169
	v_add_u32_e32 v175, v170, v169
	v_add_u32_e32 v176, v168, v171
	v_add_u32_e32 v177, v170, v171
	ds_read_b128 v[150:153], v174
	ds_read_b128 v[154:157], v174 offset:4096
	ds_read_b128 v[158:161], v175 offset:16384
	ds_read_b128 v[162:165], v175 offset:20480
	ds_read_b128 v[180:183], v176
	ds_read_b128 v[184:187], v176 offset:4096
	ds_read_b128 v[188:191], v177 offset:16384
	ds_read_b128 v[192:195], v177 offset:20480
	s_mov_b32 m0, s58
	s_nop 0
	global_load_lds_dwordx4 v136, s[2:3]
	global_load_lds_dwordx4 v137, s[2:3] offset:1024
	global_load_lds_dwordx4 v138, s[2:3] offset:2048
	global_load_lds_dwordx4 v139, s[2:3] offset:3072
	s_add_u32 s2, s2, 0x80
	s_addc_u32 s3, s3, 0
	s_waitcnt lgkmcnt(5)
	v_mfma_f32_32x32x16_bf16 v[50:65], v[150:153], v[158:161], v[50:65]
	v_add_u32_e32 v178, v168, v172
	v_add_u32_e32 v179, v170, v172
	s_waitcnt lgkmcnt(4)
	v_mfma_f32_32x32x16_bf16 v[34:49], v[150:153], v[162:165], v[34:49]
	v_mfma_f32_32x32x16_bf16 v[18:33], v[154:157], v[158:161], v[18:33]
	v_mfma_f32_32x32x16_bf16 v[2:17], v[154:157], v[162:165], v[2:17]
	s_cmp_lt_u32 s43, 2
	s_cbranch_scc1 .Lkce
	s_cmp_lt_u32 s100, 1
	s_cbranch_scc1 .Lkce
	v_add_f32_e32 v222, v222, v66
	v_add_f32_e32 v223, v223, v67
	v_add_f32_e32 v224, v224, v68
	v_add_f32_e32 v225, v225, v69
	v_add_f32_e32 v226, v226, v70
	v_add_f32_e32 v227, v227, v71
	v_add_f32_e32 v228, v228, v72
	v_add_f32_e32 v229, v229, v73
	s_cmp_lt_u32 s100, 2
	s_cbranch_scc1 .Lkce
	v_add_f32_e32 v222, v222, v74
	v_add_f32_e32 v223, v223, v75
	v_add_f32_e32 v224, v224, v76
	v_add_f32_e32 v225, v225, v77
	v_add_f32_e32 v226, v226, v78
	v_add_f32_e32 v227, v227, v79
	v_add_f32_e32 v228, v228, v80
	v_add_f32_e32 v229, v229, v81

; DI f32x16 mfma32(bf16x8 a, bf16x8 b, f32x16 c) { return __builtin_amdgcn_mfma_f32_32x32x16_bf16(a, b, c, 0, 0, 0); }
; DI void kmean_item(const float* __restrict__ base, const int* __restrict__ pt, int b, int n, float* __restrict__ outp, char* sm) {
;     ...
;         for (int rr = 0; rr < 32; ++rr) {
;             a0 += __builtin_nontemporal_load((const f32x4*)(rp + (size_t)rr * 4096));
;             a1 += __builtin_nontemporal_load((const f32x4*)(rp + (size_t)rr * 4096 + 256));
;         }
; template <class AL>
; DI void gemm_mainloop(f32x16 (&acc)[2][2], GemmRegs<AL>& G, bool pre, const AL& al, const u16* __restrict__ Bt, int ldb, int n0, int nk, char* sm,
;                       bool has_next, const AL& aln, int n0n) {
;     ...
;         auto rd = [&](int set, int ks) {
; #pragma unroll
;             for (int mi = 0; mi < 2; ++mi) { const int row = wm * 64 + mi * 32 + r; a[set][mi] = *(const bf16x8*)(cA + row * 128 + (((2 * ks + h) ^ ((row >> 1) & 7)) << 4)); }
; #pragma unroll
;             for (int ni = 0; ni < 2; ++ni) { const int row = wn * 64 + ni * 32 + r; b[set][ni] = *(const bf16x8*)(cB + row * 128 + (((2 * ks + h) ^ ((row >> 1) & 7)) << 4)); }
;         };
;         auto mm = [&](int set) {
; #pragma unroll
;             for (int mi = 0; mi < 2; ++mi)
; #pragma unroll
;                 for (int ni = 0; ni < 2; ++ni) acc[mi][ni] = mfma32(a[set][mi], b[set][ni], acc[mi][ni]);
;         };
;         rd(0, 0); rd(1, 1);
;         __builtin_amdgcn_sched_barrier(0);
;         mm(0); rd(0, 2);
;         __builtin_amdgcn_sched_barrier(0);
;         mm(1); rd(1, 3);
;         __builtin_amdgcn_sched_barrier(0);
;         mm(0); mm(1);
.Lg1_skipA:
	s_waitcnt lgkmcnt(5)
	v_mfma_f32_32x32x16_bf16 v[50:65], v[150:153], v[158:161], v[50:65]
	s_waitcnt lgkmcnt(4)
	v_mfma_f32_32x32x16_bf16 v[34:49], v[150:153], v[162:165], v[34:49]
	v_mfma_f32_32x32x16_bf16 v[18:33], v[154:157], v[158:161], v[18:33]
	v_mfma_f32_32x32x16_bf16 v[2:17], v[154:157], v[162:165], v[2:17]
	s_cmp_lt_u32 s43, 2
	s_cbranch_scc1 .Lkco
	s_cmp_lt_u32 s100, 1
	s_cbranch_scc1 .Lkco
	v_add_f32_e32 v222, v222, v82
	v_add_f32_e32 v223, v223, v83
	v_add_f32_e32 v224, v224, v84
	v_add_f32_e32 v225, v225, v85
	v_add_f32_e32 v226, v226, v86
	v_add_f32_e32 v227, v227, v87
	v_add_f32_e32 v228, v228, v88
	v_add_f32_e32 v229, v229, v89
	s_cmp_lt_u32 s100, 2
	s_cbranch_scc1 .Lkco
	v_add_f32_e32 v222, v222, v90
	v_add_f32_e32 v223, v223, v91
	v_add_f32_e32 v224, v224, v92
	v_add_f32_e32 v225, v225, v93
	v_add_f32_e32 v226, v226, v94
	v_add_f32_e32 v227, v227, v95
	v_add_f32_e32 v228, v228, v96
	v_add_f32_e32 v229, v229, v97

; DI void kmean_item(const float* __restrict__ base, const int* __restrict__ pt, int b, int n, float* __restrict__ outp, char* sm) {
;     ...
;         for (int rr = 0; rr < 32; ++rr) {
;             a0 += __builtin_nontemporal_load((const f32x4*)(rp + (size_t)rr * 4096));
;             a1 += __builtin_nontemporal_load((const f32x4*)(rp + (size_t)rr * 4096 + 256));
;         }
.Lkwob:
	s_barrier
	s_add_i32 s43, s43, 2
	s_cmp_lt_u32 s43, 16
	s_cbranch_scc1 .Lg1_loop
	s_setprio 0
	s_cmp_lt_u32 s100, 1
	s_cbranch_scc1 .Lkf_done
	s_waitcnt vmcnt(0)
	s_cmp_lt_u32 s100, 1
	s_cbranch_scc1 .Lkcfe
	v_add_f32_e32 v222, v222, v66
	v_add_f32_e32 v223, v223, v67
	v_add_f32_e32 v224, v224, v68
	v_add_f32_e32 v225, v225, v69
	v_add_f32_e32 v226, v226, v70
	v_add_f32_e32 v227, v227, v71
	v_add_f32_e32 v228, v228, v72
	v_add_f32_e32 v229, v229, v73
	s_cmp_lt_u32 s100, 2
	s_cbranch_scc1 .Lkcfe
	v_add_f32_e32 v222, v222, v74
	v_add_f32_e32 v223, v223, v75
	v_add_f32_e32 v224, v224, v76
	v_add_f32_e32 v225, v225, v77
	v_add_f32_e32 v226, v226, v78
	v_add_f32_e32 v227, v227, v79
	v_add_f32_e32 v228, v228, v80
	v_add_f32_e32 v229, v229, v81
.Lkcfe:
	s_cmp_lt_u32 s100, 1
	s_cbranch_scc1 .Lkcfo
	v_add_f32_e32 v222, v222, v82
	v_add_f32_e32 v223, v223, v83
	v_add_f32_e32 v224, v224, v84
	v_add_f32_e32 v225, v225, v85
	v_add_f32_e32 v226, v226, v86
	v_add_f32_e32 v227, v227, v87
	v_add_f32_e32 v228, v228, v88
	v_add_f32_e32 v229, v229, v89
	s_cmp_lt_u32 s100, 2
	s_cbranch_scc1 .Lkcfo
	v_add_f32_e32 v222, v222, v90
	v_add_f32_e32 v223, v223, v91
	v_add_f32_e32 v224, v224, v92
	v_add_f32_e32 v225, v225, v93
	v_add_f32_e32 v226, v226, v94
	v_add_f32_e32 v227, v227, v95
	v_add_f32_e32 v228, v228, v96
	v_add_f32_e32 v229, v229, v97
